# final sample-row pass: g_final chunk loads issued up front, the four output stores go out back to back
# baseline (speedup 1.0000x reference)
; #define MOD WSP(float, WS_MOD)
; #define X1 WSP(float, WS_X1)
; __device__ __forceinline__ void sample_rows_p11(Frame& F, const float* X1, const float* Z, const float* g, const float* MOD, float* out) {
;     ...
;     for (int r = gw; r < NSR; r += NGW) {
;         const int m = NPR + r; const float* modr = MOD + (size_t)modrow(m) * NMOD;
;         f32x4 v[4]; float ss = 0.f;
; #pragma unroll
;         for (int j = 0; j < 4; ++j) { const int col = 4 * lane + 256 * j; f32x4 z = *(const f32x4*)(Z + (size_t)r * DM + col);
; #pragma unroll
;             for (int ks = 1; ks < KS_DOWN; ++ks) z += *(const f32x4*)(Z + ((size_t)ks * NSR + r) * DM + col);
;             v[j] = *(const f32x4*)(X1 + (size_t)m * DM + col) + *(const f32x4*)(modr + 5120 + col) * z;
;             ss += (v[j][0] * v[j][0] + v[j][1] * v[j][1]) + (v[j][2] * v[j][2] + v[j][3] * v[j][3]); }
.LBB0_1718:
	s_nop 0
	v_lshl_add_u64 v[6:7], s[4:5], 0, v[2:3]
	v_add_co_u32_e32 v40, vcc, s7, v6
	s_add_i32 s24, s6, 0xffff8000
	s_nop 0
	v_addc_co_u32_e32 v41, vcc, 0, v7, vcc
	v_add_co_u32_e32 v56, vcc, s14, v6
	s_lshr_b32 s1, s24, 3
	s_nop 0
	v_addc_co_u32_e32 v57, vcc, 0, v7, vcc
	v_add_co_u32_e32 v72, vcc, s15, v6
	s_ashr_i32 s0, s6, 11
	s_nop 0
	v_addc_co_u32_e32 v73, vcc, 0, v7, vcc
	v_add_co_u32_e32 v88, vcc, s16, v6
	s_add_i32 s1, s1, 16
	s_nop 0
	v_addc_co_u32_e32 v89, vcc, 0, v7, vcc
	v_add_co_u32_e32 v104, vcc, s17, v6
	s_cmp_lt_i32 s24, 0
	s_nop 0
	v_addc_co_u32_e32 v105, vcc, 0, v7, vcc
	v_add_co_u32_e32 v120, vcc, s18, v6
	global_load_dwordx4 v[20:23], v[4:5], off
	global_load_dwordx4 v[184:187], v[4:5], off offset:1024
	global_load_dwordx4 v[188:191], v[4:5], off offset:2048
	global_load_dwordx4 v[192:195], v[4:5], off offset:3072
	s_nop 0
	v_addc_co_u32_e32 v121, vcc, 0, v7, vcc
	v_add_co_u32_e32 v132, vcc, s19, v6
	global_load_dwordx4 v[24:27], v[40:41], off
	global_load_dwordx4 v[28:31], v[40:41], off offset:1024
	global_load_dwordx4 v[32:35], v[40:41], off offset:2048
	global_load_dwordx4 v[36:39], v[40:41], off offset:3072
	s_cselect_b32 s0, s0, s1
	global_load_dwordx4 v[40:43], v[56:57], off
	global_load_dwordx4 v[44:47], v[56:57], off offset:1024
	global_load_dwordx4 v[48:51], v[56:57], off offset:2048
	global_load_dwordx4 v[52:55], v[56:57], off offset:3072
	v_addc_co_u32_e32 v133, vcc, 0, v7, vcc
	s_mul_hi_i32 s1, s0, 0x6000
	s_mulk_i32 s0, 0x6000
	global_load_dwordx4 v[56:59], v[72:73], off
	global_load_dwordx4 v[60:63], v[72:73], off offset:1024
	global_load_dwordx4 v[64:67], v[72:73], off offset:2048
	global_load_dwordx4 v[68:71], v[72:73], off offset:3072
	v_add_co_u32_e32 v152, vcc, s20, v6
	v_lshl_add_u64 v[8:9], s[10:11], 0, v[2:3]
	s_add_u32 s0, s2, s0
	global_load_dwordx4 v[72:75], v[88:89], off
	global_load_dwordx4 v[76:79], v[88:89], off offset:1024
	global_load_dwordx4 v[80:83], v[88:89], off offset:2048
	global_load_dwordx4 v[84:87], v[88:89], off offset:3072
	v_addc_co_u32_e32 v153, vcc, 0, v7, vcc
	s_addc_u32 s1, s3, s1
	global_load_dwordx4 v[88:91], v[104:105], off
	global_load_dwordx4 v[92:95], v[104:105], off offset:1024
	global_load_dwordx4 v[96:99], v[104:105], off offset:2048
	global_load_dwordx4 v[100:103], v[104:105], off offset:3072
	v_add_co_u32_e32 v168, vcc, s21, v8
	v_lshl_add_u64 v[164:165], v[0:1], 2, s[0:1]
	global_load_dwordx4 v[104:107], v[120:121], off
	global_load_dwordx4 v[108:111], v[120:121], off offset:1024
	global_load_dwordx4 v[112:115], v[120:121], off offset:2048
	global_load_dwordx4 v[116:119], v[120:121], off offset:3072
	v_addc_co_u32_e32 v169, vcc, 0, v9, vcc
	global_load_dwordx4 v[120:123], v[132:133], off
	global_load_dwordx4 v[124:127], v[132:133], off offset:1024
	global_load_dwordx4 v[128:131], v[132:133], off offset:2048
	s_nop 0
	global_load_dwordx4 v[132:135], v[132:133], off offset:3072
	v_add_co_u32_e32 v172, vcc, s22, v164
	v_lshl_add_u64 v[176:177], v[164:165], 0, s[12:13]
	global_load_dwordx4 v[6:9], v[152:153], off
	global_load_dwordx4 v[136:139], v[152:153], off offset:1024
	global_load_dwordx4 v[140:143], v[176:177], off offset:1024
	global_load_dwordx4 v[144:147], v[176:177], off offset:2048
	global_load_dwordx4 v[148:151], v[152:153], off offset:2048
	s_nop 0
	global_load_dwordx4 v[152:155], v[152:153], off offset:3072
	s_nop 0
	global_load_dwordx4 v[156:159], v[168:169], off
	global_load_dwordx4 v[160:163], v[168:169], off offset:1024
	v_addc_co_u32_e32 v173, vcc, 0, v165, vcc
	global_load_dwordx4 v[164:167], v[168:169], off offset:2048
	s_nop 0
	global_load_dwordx4 v[168:171], v[168:169], off offset:3072
	s_nop 0
	global_load_dwordx4 v[172:175], v[172:173], off
	s_nop 0
	global_load_dwordx4 v[176:179], v[176:177], off offset:3072
	v_lshl_add_u64 v[10:11], s[8:9], 0, v[2:3]
	s_add_u32 s4, s4, 0x400000
	s_addc_u32 s5, s5, 0
	s_addk_i32 s6, 0x400
	s_add_u32 s8, s8, 0x400000
	s_addc_u32 s9, s9, 0
	s_add_u32 s10, s10, 0x400000
	s_addc_u32 s11, s11, 0
	s_cmp_gt_i32 s24, -1
	s_waitcnt vmcnt(35)
	v_pk_add_f32 v[26:27], v[26:27], v[42:43]
	v_pk_add_f32 v[24:25], v[24:25], v[40:41]
	s_waitcnt vmcnt(34)
	v_pk_add_f32 v[30:31], v[30:31], v[46:47]
	v_pk_add_f32 v[28:29], v[28:29], v[44:45]
	s_waitcnt vmcnt(33)
	v_pk_add_f32 v[34:35], v[34:35], v[50:51]
	v_pk_add_f32 v[32:33], v[32:33], v[48:49]
	s_waitcnt vmcnt(32)
	v_pk_add_f32 v[38:39], v[38:39], v[54:55]
	s_waitcnt vmcnt(31)
	v_pk_add_f32 v[26:27], v[26:27], v[58:59]
	v_pk_add_f32 v[24:25], v[24:25], v[56:57]
	s_waitcnt vmcnt(30)
	v_pk_add_f32 v[30:31], v[30:31], v[62:63]
	v_pk_add_f32 v[28:29], v[28:29], v[60:61]
	s_waitcnt vmcnt(29)
	v_pk_add_f32 v[34:35], v[34:35], v[66:67]
	v_pk_add_f32 v[32:33], v[32:33], v[64:65]
	v_pk_add_f32 v[36:37], v[36:37], v[52:53]
	s_waitcnt vmcnt(28)
	v_pk_add_f32 v[38:39], v[38:39], v[70:71]
	s_waitcnt vmcnt(27)
	v_pk_add_f32 v[26:27], v[26:27], v[74:75]
	v_pk_add_f32 v[24:25], v[24:25], v[72:73]
	s_waitcnt vmcnt(26)
	v_pk_add_f32 v[30:31], v[30:31], v[78:79]
	v_pk_add_f32 v[28:29], v[28:29], v[76:77]
	s_waitcnt vmcnt(25)
	v_pk_add_f32 v[34:35], v[34:35], v[82:83]
	v_pk_add_f32 v[32:33], v[32:33], v[80:81]
	v_pk_add_f32 v[36:37], v[36:37], v[68:69]
	s_waitcnt vmcnt(24)
	v_pk_add_f32 v[38:39], v[38:39], v[86:87]
	s_waitcnt vmcnt(23)
	v_pk_add_f32 v[26:27], v[26:27], v[90:91]
	v_pk_add_f32 v[24:25], v[24:25], v[88:89]
	s_waitcnt vmcnt(22)
	v_pk_add_f32 v[30:31], v[30:31], v[94:95]
	v_pk_add_f32 v[28:29], v[28:29], v[92:93]
	s_waitcnt vmcnt(21)
	v_pk_add_f32 v[34:35], v[34:35], v[98:99]
	v_pk_add_f32 v[32:33], v[32:33], v[96:97]
	v_pk_add_f32 v[36:37], v[36:37], v[84:85]
	s_waitcnt vmcnt(20)
; #define GAS __attribute__((address_space(1)))
; #define X1 WSP(float, WS_X1)
; __device__ __forceinline__ void sample_rows_p11(Frame& F, const float* X1, const float* Z, const float* g, const float* MOD, float* out) {
;     ...
;             v[j] = *(const f32x4*)(X1 + (size_t)m * DM + col) + *(const f32x4*)(modr + 5120 + col) * z;
;             ss += (v[j][0] * v[j][0] + v[j][1] * v[j][1]) + (v[j][2] * v[j][2] + v[j][3] * v[j][3]); }
;         const float rstd = 1.f / sqrtf(wave_sum(ss) * (1.f / DM) + EPS);
; #pragma unroll
;         for (int j = 0; j < 4; ++j) { const int col = 4 * lane + 256 * j; *(GAS f32x4*)(out + (size_t)m * DM + col) = (v[j] * rstd) * *(const f32x4*)(g + col); }
	v_pk_add_f32 v[38:39], v[38:39], v[102:103]
	s_waitcnt vmcnt(19)
	v_pk_add_f32 v[26:27], v[26:27], v[106:107]
	v_pk_add_f32 v[24:25], v[24:25], v[104:105]
	s_waitcnt vmcnt(18)
	v_pk_add_f32 v[30:31], v[30:31], v[110:111]
	v_pk_add_f32 v[28:29], v[28:29], v[108:109]
	s_waitcnt vmcnt(17)
	v_pk_add_f32 v[34:35], v[34:35], v[114:115]
	v_pk_add_f32 v[32:33], v[32:33], v[112:113]
	v_pk_add_f32 v[36:37], v[36:37], v[100:101]
	s_waitcnt vmcnt(16)
	v_pk_add_f32 v[38:39], v[38:39], v[118:119]
	s_waitcnt vmcnt(15)
	v_pk_add_f32 v[26:27], v[26:27], v[122:123]
	v_pk_add_f32 v[24:25], v[24:25], v[120:121]
	s_waitcnt vmcnt(14)
	v_pk_add_f32 v[30:31], v[30:31], v[126:127]
	v_pk_add_f32 v[28:29], v[28:29], v[124:125]
	s_waitcnt vmcnt(13)
	v_pk_add_f32 v[34:35], v[34:35], v[130:131]
	v_pk_add_f32 v[32:33], v[32:33], v[128:129]
	v_pk_add_f32 v[36:37], v[36:37], v[116:117]
	s_waitcnt vmcnt(12)
	v_pk_add_f32 v[38:39], v[38:39], v[134:135]
	s_waitcnt vmcnt(11)
	v_pk_add_f32 v[8:9], v[26:27], v[8:9]
	v_pk_add_f32 v[6:7], v[24:25], v[6:7]
	s_waitcnt vmcnt(10)
	v_pk_add_f32 v[24:25], v[30:31], v[138:139]
	v_pk_add_f32 v[26:27], v[28:29], v[136:137]
	s_waitcnt vmcnt(7)
	v_pk_add_f32 v[28:29], v[34:35], v[150:151]
	v_pk_add_f32 v[30:31], v[32:33], v[148:149]
	v_pk_add_f32 v[36:37], v[36:37], v[132:133]
	s_waitcnt vmcnt(6)
	v_pk_add_f32 v[32:33], v[38:39], v[154:155]
	s_waitcnt vmcnt(4)
	v_pk_fma_f32 v[24:25], v[24:25], v[142:143], v[162:163]
	v_pk_fma_f32 v[26:27], v[26:27], v[140:141], v[160:161]
	s_waitcnt vmcnt(3)
	v_pk_fma_f32 v[28:29], v[28:29], v[146:147], v[166:167]
	v_pk_fma_f32 v[30:31], v[30:31], v[144:145], v[164:165]
	s_waitcnt vmcnt(1)
	v_pk_fma_f32 v[8:9], v[8:9], v[174:175], v[158:159]
	v_pk_fma_f32 v[6:7], v[6:7], v[172:173], v[156:157]
	v_pk_add_f32 v[34:35], v[36:37], v[152:153]
	v_pk_mul_f32 v[36:37], v[24:25], v[24:25]
	v_pk_mul_f32 v[38:39], v[26:27], v[26:27]
	s_waitcnt vmcnt(0)
	v_pk_fma_f32 v[32:33], v[32:33], v[178:179], v[170:171]
	v_mul_f32_e32 v40, v31, v31
	v_mul_f32_e32 v42, v29, v29
	v_pk_mul_f32 v[44:45], v[8:9], v[8:9]
	v_pk_mul_f32 v[46:47], v[6:7], v[6:7]
	v_pk_mov_b32 v[48:49], v[38:39], v[36:37] op_sel:[1,0]
	v_mov_b32_e32 v39, v37
	v_mul_f32_e32 v52, v32, v32
	v_mul_f32_e32 v53, v33, v33
	v_pk_fma_f32 v[36:37], v[30:31], v[30:31], v[40:41] op_sel_hi:[1,1,0]
	v_pk_fma_f32 v[40:41], v[28:29], v[28:29], v[42:43] op_sel_hi:[1,1,0]
	v_pk_mov_b32 v[42:43], v[46:47], v[44:45] op_sel:[1,0]
	v_mov_b32_e32 v47, v45
	v_pk_fma_f32 v[34:35], v[34:35], v[176:177], v[168:169]
	v_pk_add_f32 v[38:39], v[48:49], v[38:39]
	v_mov_b32_e32 v37, v52
	v_mov_b32_e32 v41, v53
	v_pk_add_f32 v[42:43], v[42:43], v[46:47]
	v_mul_f32_e32 v50, v34, v34
	v_mul_f32_e32 v51, v35, v35
	v_pk_add_f32 v[38:39], v[38:39], v[38:39] op_sel:[0,1] op_sel_hi:[1,0]
	v_pk_add_f32 v[36:37], v[36:37], v[40:41]
	v_pk_add_f32 v[40:41], v[42:43], v[42:43] op_sel:[0,1] op_sel_hi:[1,0]
	v_mov_b32_e32 v39, v51
	v_mov_b32_e32 v41, v50
	v_pk_add_f32 v[38:39], v[40:41], v[38:39]
	s_nop 0
	v_pk_add_f32 v[36:37], v[38:39], v[36:37]
	s_nop 0
	v_add_f32_e32 v36, v36, v37
	ds_bpermute_b32 v37, v12, v36
	s_waitcnt lgkmcnt(0)
	v_add_f32_e32 v36, v36, v37
	ds_bpermute_b32 v37, v13, v36
	s_waitcnt lgkmcnt(0)
	v_add_f32_e32 v36, v36, v37
	ds_bpermute_b32 v37, v14, v36
	s_waitcnt lgkmcnt(0)
	v_add_f32_e32 v36, v36, v37
	ds_bpermute_b32 v37, v15, v36
	s_waitcnt lgkmcnt(0)
	v_add_f32_e32 v36, v36, v37
	ds_bpermute_b32 v37, v16, v36
	s_waitcnt lgkmcnt(0)
	v_add_f32_e32 v36, v36, v37
	ds_bpermute_b32 v37, v17, v36
	s_waitcnt lgkmcnt(0)
	v_add_f32_e32 v36, v36, v37
	v_fmamk_f32 v36, v36, 0x3a800000, v18
	v_mul_f32_e32 v37, 0x4f800000, v36
	v_cmp_gt_f32_e32 vcc, s23, v36
	s_nop 1
	v_cndmask_b32_e32 v36, v36, v37, vcc
	v_sqrt_f32_e32 v37, v36
	s_nop 0
	v_add_u32_e32 v38, -1, v37
	v_add_u32_e32 v39, 1, v37
	v_fma_f32 v40, -v38, v37, v36
	v_fma_f32 v41, -v39, v37, v36
	v_cmp_ge_f32_e64 s[0:1], 0, v40
	s_nop 1
	v_cndmask_b32_e64 v37, v37, v38, s[0:1]
	v_cmp_lt_f32_e64 s[0:1], 0, v41
	s_nop 1
	v_cndmask_b32_e64 v37, v37, v39, s[0:1]
	v_mul_f32_e32 v38, 0x37800000, v37
	v_cndmask_b32_e32 v37, v37, v38, vcc
	v_cmp_class_f32_e32 vcc, v36, v19
	s_nop 1
	v_cndmask_b32_e32 v36, v37, v36, vcc
	v_div_scale_f32 v37, s[0:1], v36, v36, 1.0
	v_rcp_f32_e32 v39, v37
	v_div_scale_f32 v38, vcc, 1.0, v36, 1.0
	v_fma_f32 v40, -v37, v39, 1.0
	v_fmac_f32_e32 v39, v40, v39
	v_mul_f32_e32 v40, v38, v39
	v_fma_f32 v41, -v37, v40, v38
	v_fmac_f32_e32 v40, v41, v39
	v_fma_f32 v37, -v37, v40, v38
	v_div_fmas_f32 v37, v37, v39, v40
	v_div_fixup_f32 v36, v37, v36, 1.0
	v_pk_mul_f32 v[6:7], v[6:7], v[36:37] op_sel_hi:[1,0]
	v_pk_mul_f32 v[8:9], v[8:9], v[36:37] op_sel_hi:[1,0]
	v_pk_mul_f32 v[6:7], v[20:21], v[6:7]
	v_pk_mul_f32 v[8:9], v[22:23], v[8:9]
	global_store_dwordx4 v[10:11], v[6:9], off
	v_pk_mul_f32 v[20:21], v[24:25], v[36:37] op_sel_hi:[1,0]
	v_pk_mul_f32 v[22:23], v[26:27], v[36:37] op_sel_hi:[1,0]
	v_pk_mul_f32 v[198:199], v[186:187], v[20:21]
	v_pk_mul_f32 v[196:197], v[184:185], v[22:23]
	global_store_dwordx4 v[10:11], v[196:199], off offset:1024
	v_pk_mul_f32 v[20:21], v[28:29], v[36:37] op_sel_hi:[1,0]
	v_pk_mul_f32 v[22:23], v[30:31], v[36:37] op_sel_hi:[1,0]
	v_pk_mul_f32 v[202:203], v[190:191], v[20:21]
	v_pk_mul_f32 v[200:201], v[188:189], v[22:23]
	global_store_dwordx4 v[10:11], v[200:203], off offset:2048
	v_pk_mul_f32 v[20:21], v[32:33], v[36:37] op_sel_hi:[1,0]
	v_pk_mul_f32 v[22:23], v[34:35], v[36:37] op_sel_hi:[1,0]
	v_pk_mul_f32 v[206:207], v[194:195], v[20:21]
	v_pk_mul_f32 v[204:205], v[192:193], v[22:23]
	global_store_dwordx4 v[10:11], v[204:207], off offset:3072
	s_cbranch_scc0 .LBB0_1718
